# final output stores write-through (no dirty lines left for the end-of-kernel flush)
# speedup vs baseline: 1.0053x; 1.0028x over previous
.LBB0_652:
	s_or_b64 exec, exec, s[2:3]
	v_lshlrev_b64 v[172:173], 2, v[128:129]
	s_waitcnt lgkmcnt(0)
	s_barrier
	v_lshl_add_u64 v[188:189], s[82:83], 0, v[172:173]
	global_load_dwordx4 v[190:193], v[188:189], off
	global_load_dwordx4 v[196:199], v[188:189], off offset:64
	v_or_b32_e32 v171, v171, v161
	v_lshl_add_u64 v[238:239], s[84:85], 0, v[172:173]
	global_load_dwordx4 v[136:139], v[238:239], off
	global_load_dwordx4 v[132:135], v[238:239], off offset:64
	global_load_dwordx4 v[128:131], v[238:239], off offset:512
	s_waitcnt lgkmcnt(0)
	v_or_b32_e32 v171, v141, v171
	v_mov_b32_e32 v141, 0x7fc00000
	s_waitcnt vmcnt(0)
	v_div_scale_f32 v161, s[0:1], v190, v190, 1.0
	v_div_scale_f32 v203, s[0:1], v191, v191, 1.0
	v_rcp_f32_e32 v231, v161
	v_rcp_f32_e32 v244, v203
	v_div_scale_f32 v213, s[2:3], v192, v192, 1.0
	v_div_scale_f32 v219, s[2:3], v193, v193, 1.0
	v_rcp_f32_e32 v245, v213
	v_rcp_f32_e32 v246, v219
	v_fma_f32 v204, -v161, v231, 1.0
	v_fma_f32 v205, -v203, v244, 1.0
	v_div_scale_f32 v183, vcc, 1.0, v190, 1.0
	v_div_scale_f32 v212, s[0:1], 1.0, v191, 1.0
	v_fmac_f32_e32 v231, v204, v231
	v_fmac_f32_e32 v244, v205, v244
	v_mul_f32_e32 v240, v183, v231
	v_mul_f32_e32 v247, v212, v244
	v_fma_f32 v206, -v213, v245, 1.0
	v_fma_f32 v207, -v219, v246, 1.0
	v_fma_f32 v204, -v161, v240, v183
	v_fma_f32 v205, -v203, v247, v212
	v_fmac_f32_e32 v245, v206, v245
	v_fmac_f32_e32 v246, v207, v246
	v_fmac_f32_e32 v240, v204, v231
	v_fmac_f32_e32 v247, v205, v244
	global_load_dwordx4 v[204:207], v[188:189], off offset:512
	v_fma_f32 v161, -v161, v240, v183
	v_div_fmas_f32 v161, v161, v231, v240
	global_load_dwordx4 v[240:243], v[188:189], off offset:576
	v_div_scale_f32 v188, s[2:3], 1.0, v192, 1.0
	v_mul_f32_e32 v189, v188, v245
	v_fma_f32 v183, -v203, v247, v212
	v_fma_f32 v203, -v213, v189, v188
	s_mov_b64 vcc, s[0:1]
	v_fmac_f32_e32 v189, v203, v245
	v_div_fmas_f32 v183, v183, v244, v247
	v_div_scale_f32 v203, s[0:1], 1.0, v193, 1.0
	v_fma_f32 v188, -v213, v189, v188
	s_mov_b64 vcc, s[2:3]
	v_div_fmas_f32 v188, v188, v245, v189
	v_mul_f32_e32 v189, v203, v246
	v_fma_f32 v213, -v219, v189, v203
	v_fmac_f32_e32 v189, v213, v246
	v_div_scale_f32 v212, s[4:5], v196, v196, 1.0
	v_fma_f32 v203, -v219, v189, v203
	s_mov_b64 vcc, s[0:1]
	v_div_scale_f32 v219, s[4:5], v197, v197, 1.0
	v_div_fmas_f32 v189, v203, v246, v189
	v_rcp_f32_e32 v203, v212
	v_div_fixup_f32 v190, v161, v190, 1.0
	v_rcp_f32_e32 v161, v219
	v_div_fixup_f32 v192, v188, v192, 1.0
	v_fma_f32 v188, -v212, v203, 1.0
	v_div_scale_f32 v213, s[2:3], 1.0, v196, 1.0
	v_div_fixup_f32 v193, v189, v193, 1.0
	v_fma_f32 v189, -v219, v161, 1.0
	v_fmac_f32_e32 v203, v188, v203
	v_div_fixup_f32 v191, v183, v191, 1.0
	v_div_scale_f32 v183, s[0:1], 1.0, v197, 1.0
	v_fmac_f32_e32 v161, v189, v161
	v_mul_f32_e32 v188, v213, v203
	v_mul_f32_e32 v189, v183, v161
	v_fma_f32 v231, -v212, v188, v213
	v_fmac_f32_e32 v188, v231, v203
	v_fma_f32 v231, -v219, v189, v183
	v_fmac_f32_e32 v189, v231, v161
	v_div_scale_f32 v231, s[4:5], v198, v198, 1.0
	v_fma_f32 v212, -v212, v188, v213
	v_rcp_f32_e32 v213, v231
	s_mov_b64 vcc, s[2:3]
	v_fma_f32 v183, -v219, v189, v183
	v_div_fmas_f32 v188, v212, v203, v188
	s_mov_b64 vcc, s[0:1]
	v_div_fmas_f32 v161, v183, v161, v189
	v_div_fixup_f32 v189, v161, v197, 1.0
	v_fma_f32 v161, -v231, v213, 1.0
	v_fmac_f32_e32 v213, v161, v213
	v_div_scale_f32 v161, vcc, 1.0, v198, 1.0
	v_mul_f32_e32 v183, v161, v213
	v_div_scale_f32 v197, s[0:1], v199, v199, 1.0
	v_div_fixup_f32 v188, v188, v196, 1.0
	v_fma_f32 v196, -v231, v183, v161
	v_rcp_f32_e32 v203, v197
	v_fmac_f32_e32 v183, v196, v213
	v_fma_f32 v161, -v231, v183, v161
	v_div_fmas_f32 v161, v161, v213, v183
	v_div_fixup_f32 v196, v161, v198, 1.0
	v_fma_f32 v161, -v197, v203, 1.0
	v_fmac_f32_e32 v203, v161, v203
	v_div_scale_f32 v161, vcc, 1.0, v199, 1.0
	v_mul_f32_e32 v183, v161, v203
	v_fma_f32 v198, -v197, v183, v161
	v_fmac_f32_e32 v183, v198, v203
	v_fma_f32 v161, -v197, v183, v161
	v_div_fmas_f32 v161, v161, v203, v183
	s_waitcnt vmcnt(1)
	v_div_scale_f32 v198, s[0:1], v204, v204, 1.0
	v_rcp_f32_e32 v212, v198
	v_div_fixup_f32 v197, v161, v199, 1.0
	v_lshlrev_b32_e32 v246, 16, v227
	v_and_b32_e32 v247, 0xffff0000, v227
	v_fma_f32 v161, -v198, v212, 1.0
	v_fmac_f32_e32 v212, v161, v212
	v_div_scale_f32 v161, vcc, 1.0, v204, 1.0
	v_mul_f32_e32 v183, v161, v212
	v_fma_f32 v199, -v198, v183, v161
	v_fmac_f32_e32 v183, v199, v212
	v_div_scale_f32 v199, s[0:1], v205, v205, 1.0
	v_rcp_f32_e32 v203, v199
	v_fma_f32 v161, -v198, v183, v161
	v_div_fmas_f32 v161, v161, v212, v183
	v_div_fixup_f32 v198, v161, v204, 1.0
	v_fma_f32 v161, -v199, v203, 1.0
	v_fmac_f32_e32 v203, v161, v203
	v_div_scale_f32 v161, vcc, 1.0, v205, 1.0
	v_mul_f32_e32 v183, v161, v203
	v_fma_f32 v204, -v199, v183, v161
	v_fmac_f32_e32 v183, v204, v203
	v_div_scale_f32 v204, s[0:1], v206, v206, 1.0
	v_rcp_f32_e32 v212, v204
	v_fma_f32 v161, -v199, v183, v161
	v_div_fmas_f32 v161, v161, v203, v183
	v_div_fixup_f32 v199, v161, v205, 1.0
	v_fma_f32 v161, -v204, v212, 1.0
	v_fmac_f32_e32 v212, v161, v212
	v_div_scale_f32 v161, vcc, 1.0, v206, 1.0
	v_mul_f32_e32 v183, v161, v212
	v_fma_f32 v203, -v204, v183, v161
	v_fmac_f32_e32 v183, v203, v212
	v_div_scale_f32 v203, s[0:1], v207, v207, 1.0
	v_rcp_f32_e32 v205, v203
	v_fma_f32 v161, -v204, v183, v161
	v_div_fmas_f32 v161, v161, v212, v183
	v_div_fixup_f32 v204, v161, v206, 1.0
	v_fma_f32 v161, -v203, v205, 1.0
	v_fmac_f32_e32 v205, v161, v205
	v_div_scale_f32 v161, vcc, 1.0, v207, 1.0
	v_mul_f32_e32 v183, v161, v205
	v_fma_f32 v206, -v203, v183, v161
	v_fmac_f32_e32 v183, v206, v205
	v_fma_f32 v161, -v203, v183, v161
	s_waitcnt vmcnt(0)
	v_div_scale_f32 v203, s[0:1], v240, v240, 1.0
	v_rcp_f32_e32 v206, v203
	v_div_fmas_f32 v161, v161, v205, v183
	v_div_fixup_f32 v205, v161, v207, 1.0
	v_lshlrev_b32_e32 v244, 16, v226
	v_fma_f32 v161, -v203, v206, 1.0
	v_fmac_f32_e32 v206, v161, v206
	v_div_scale_f32 v161, vcc, 1.0, v240, 1.0
	v_mul_f32_e32 v183, v161, v206
	v_fma_f32 v207, -v203, v183, v161
	v_fmac_f32_e32 v183, v207, v206
	v_fma_f32 v161, -v203, v183, v161
	v_div_scale_f32 v203, s[0:1], v241, v241, 1.0
	v_rcp_f32_e32 v207, v203
	v_div_fmas_f32 v161, v161, v206, v183
	v_div_fixup_f32 v206, v161, v240, 1.0
	v_and_b32_e32 v245, 0xffff0000, v226
	v_fma_f32 v161, -v203, v207, 1.0
	v_fmac_f32_e32 v207, v161, v207
	v_div_scale_f32 v161, vcc, 1.0, v241, 1.0
	v_mul_f32_e32 v183, v161, v207
	v_fma_f32 v212, -v203, v183, v161
	v_fmac_f32_e32 v183, v212, v207
	v_fma_f32 v161, -v203, v183, v161
	v_div_scale_f32 v203, s[0:1], v242, v242, 1.0
	v_rcp_f32_e32 v212, v203
	v_div_fmas_f32 v161, v161, v207, v183
	v_div_fixup_f32 v207, v161, v241, 1.0
	v_add_u32_e32 v226, s16, v151
	v_fma_f32 v161, -v203, v212, 1.0
	v_fmac_f32_e32 v212, v161, v212
	v_div_scale_f32 v161, vcc, 1.0, v242, 1.0
	v_mul_f32_e32 v183, v161, v212
	v_fma_f32 v213, -v203, v183, v161
	v_fmac_f32_e32 v183, v213, v212
	v_fma_f32 v161, -v203, v183, v161
	v_div_scale_f32 v203, s[0:1], v243, v243, 1.0
	v_rcp_f32_e32 v213, v203
	v_div_fmas_f32 v161, v161, v212, v183
	v_div_fixup_f32 v212, v161, v242, 1.0
	v_ashrrev_i32_e32 v227, 31, v226
	v_fma_f32 v161, -v203, v213, 1.0
	v_fmac_f32_e32 v213, v161, v213
	v_div_scale_f32 v161, vcc, 1.0, v243, 1.0
	v_mul_f32_e32 v183, v161, v213
	v_fma_f32 v219, -v203, v183, v161
	v_fmac_f32_e32 v183, v219, v213
	v_fma_f32 v161, -v203, v183, v161
	v_div_fmas_f32 v161, v161, v213, v183
	v_div_fixup_f32 v213, v161, v243, 1.0
	v_lshl_add_u32 v161, v151, 3, 0
	v_add_u32_e32 v161, 0x2000, v161
	ds_read2_b64 v[240:243], v161 offset1:16
	v_cmp_ne_u32_e32 vcc, 0, v171
	v_pk_mul_f32 v[244:245], v[230:231], v[244:245] op_sel_hi:[0,1]
	s_waitcnt lgkmcnt(0)
	v_pk_mul_f32 v[248:249], v[124:125], v[240:241] op_sel:[0,1]
	v_pk_mul_f32 v[250:251], v[126:127], v[240:241] op_sel:[0,1]
	global_load_dwordx4 v[124:127], v[238:239], off offset:576
	v_pk_mul_f32 v[238:239], v[230:231], v[246:247] op_sel_hi:[0,1]
	v_pk_mul_f32 v[246:247], v[138:139], v[250:251]
	v_pk_mul_f32 v[248:249], v[136:137], v[248:249]
	v_pk_fma_f32 v[238:239], v[238:239], v[192:193], v[246:247]
	v_pk_fma_f32 v[244:245], v[244:245], v[190:191], v[248:249]
	v_cndmask_b32_e32 v247, v239, v141, vcc
	v_cndmask_b32_e32 v246, v238, v141, vcc
	v_lshlrev_b64 v[238:239], 12, v[226:227]
	v_lshl_add_u64 v[238:239], s[64:65], 0, v[238:239]
	v_cndmask_b32_e32 v245, v245, v141, vcc
	v_cndmask_b32_e32 v244, v244, v141, vcc
	v_lshl_add_u64 v[238:239], v[238:239], 0, v[172:173]
	global_store_dwordx4 v[238:239], v[244:247], off sc1
	v_pk_mul_f32 v[120:121], v[120:121], v[240:241] op_sel:[0,1]
	v_pk_mul_f32 v[122:123], v[122:123], v[240:241] op_sel:[0,1]
	v_lshlrev_b32_e32 v244, 16, v236
	v_and_b32_e32 v245, 0xffff0000, v236
	v_lshlrev_b32_e32 v236, 16, v237
	v_and_b32_e32 v237, 0xffff0000, v237
	v_pk_mul_f32 v[236:237], v[230:231], v[236:237] op_sel_hi:[0,1]
	v_pk_mul_f32 v[244:245], v[230:231], v[244:245] op_sel_hi:[0,1]
	v_pk_mul_f32 v[122:123], v[134:135], v[122:123]
	v_pk_mul_f32 v[120:121], v[132:133], v[120:121]
	v_pk_fma_f32 v[122:123], v[236:237], v[196:197], v[122:123]
	v_pk_fma_f32 v[120:121], v[244:245], v[188:189], v[120:121]
	v_cndmask_b32_e32 v123, v123, v141, vcc
	v_cndmask_b32_e32 v122, v122, v141, vcc
	v_cndmask_b32_e32 v121, v121, v141, vcc
	v_cndmask_b32_e32 v120, v120, v141, vcc
	global_store_dwordx4 v[238:239], v[120:123], off offset:64 sc1
	v_pk_mul_f32 v[118:119], v[118:119], v[240:241] op_sel:[0,1]
	v_pk_mul_f32 v[116:117], v[116:117], v[240:241] op_sel:[0,1]
	v_lshlrev_b32_e32 v120, 16, v234
	v_and_b32_e32 v121, 0xffff0000, v234
	v_lshlrev_b32_e32 v122, 16, v235
	v_and_b32_e32 v123, 0xffff0000, v235
	v_pk_mul_f32 v[120:121], v[230:231], v[120:121] op_sel_hi:[0,1]
	v_pk_mul_f32 v[122:123], v[230:231], v[122:123] op_sel_hi:[0,1]
	v_pk_mul_f32 v[122:123], v[122:123], v[204:205]
	v_pk_mul_f32 v[120:121], v[120:121], v[198:199]
	v_pk_fma_f32 v[118:119], v[130:131], v[118:119], v[122:123]
	v_pk_fma_f32 v[116:117], v[128:129], v[116:117], v[120:121]
	v_cndmask_b32_e32 v119, v119, v141, vcc
	v_cndmask_b32_e32 v118, v118, v141, vcc
	v_cndmask_b32_e32 v117, v117, v141, vcc
	v_cndmask_b32_e32 v116, v116, v141, vcc
	global_store_dwordx4 v[238:239], v[116:119], off offset:512 sc1
	v_pk_mul_f32 v[110:111], v[110:111], v[240:241] op_sel:[0,1]
	v_pk_mul_f32 v[108:109], v[108:109], v[240:241] op_sel:[0,1]
	v_lshlrev_b32_e32 v116, 16, v232
	v_and_b32_e32 v117, 0xffff0000, v232
	v_lshlrev_b32_e32 v118, 16, v233
	v_and_b32_e32 v119, 0xffff0000, v233
	v_pk_mul_f32 v[116:117], v[230:231], v[116:117] op_sel_hi:[0,1]
	v_pk_mul_f32 v[118:119], v[230:231], v[118:119] op_sel_hi:[0,1]
	v_pk_mul_f32 v[118:119], v[118:119], v[212:213]
	v_pk_mul_f32 v[116:117], v[116:117], v[206:207]
	v_pk_mul_f32 v[112:113], v[112:113], v[242:243] op_sel:[0,1]
	v_pk_mul_f32 v[114:115], v[114:115], v[242:243] op_sel:[0,1]
	v_pk_mul_f32 v[112:113], v[136:137], v[112:113]
	v_pk_mul_f32 v[114:115], v[138:139], v[114:115]
	v_pk_mul_f32 v[104:105], v[104:105], v[242:243] op_sel:[0,1]
	v_pk_mul_f32 v[106:107], v[106:107], v[242:243] op_sel:[0,1]
	v_pk_mul_f32 v[104:105], v[132:133], v[104:105]
	v_pk_mul_f32 v[106:107], v[134:135], v[106:107]
	v_pk_mul_f32 v[100:101], v[100:101], v[242:243] op_sel:[0,1]
	v_pk_mul_f32 v[102:103], v[102:103], v[242:243] op_sel:[0,1]
	v_pk_mul_f32 v[100:101], v[128:129], v[100:101]
	v_pk_mul_f32 v[102:103], v[130:131], v[102:103]
	v_pk_mul_f32 v[92:93], v[92:93], v[242:243] op_sel:[0,1]
	v_pk_mul_f32 v[94:95], v[94:95], v[242:243] op_sel:[0,1]
	s_waitcnt vmcnt(3)
	v_pk_fma_f32 v[108:109], v[124:125], v[108:109], v[116:117]
	v_pk_fma_f32 v[110:111], v[126:127], v[110:111], v[118:119]
	v_cndmask_b32_e32 v109, v109, v141, vcc
	v_cndmask_b32_e32 v111, v111, v141, vcc
	v_cndmask_b32_e32 v110, v110, v141, vcc
	v_cndmask_b32_e32 v108, v108, v141, vcc
	global_store_dwordx4 v[238:239], v[108:111], off offset:576 sc1
	v_add_u32_e32 v116, 16, v226
	v_ashrrev_i32_e32 v117, 31, v116
	v_lshlrev_b32_e32 v108, 16, v228
	v_and_b32_e32 v109, 0xffff0000, v228
	v_lshlrev_b32_e32 v110, 16, v229
	v_and_b32_e32 v111, 0xffff0000, v229
	v_pk_mul_f32 v[108:109], v[218:219], v[108:109] op_sel_hi:[0,1]
	v_pk_mul_f32 v[110:111], v[218:219], v[110:111] op_sel_hi:[0,1]
	v_pk_fma_f32 v[108:109], v[108:109], v[190:191], v[112:113]
	v_lshlrev_b64 v[112:113], 12, v[116:117]
	v_pk_fma_f32 v[110:111], v[110:111], v[192:193], v[114:115]
	v_lshl_add_u64 v[112:113], s[64:65], 0, v[112:113]
	v_cndmask_b32_e32 v111, v111, v141, vcc
	v_cndmask_b32_e32 v110, v110, v141, vcc
	v_cndmask_b32_e32 v109, v109, v141, vcc
	v_cndmask_b32_e32 v108, v108, v141, vcc
	v_lshl_add_u64 v[112:113], v[112:113], 0, v[172:173]
	global_store_dwordx4 v[112:113], v[108:111], off sc1
	v_pk_mul_f32 v[94:95], v[126:127], v[94:95]
	v_pk_mul_f32 v[92:93], v[124:125], v[92:93]
	v_lshlrev_b32_e32 v108, 16, v224
	v_and_b32_e32 v109, 0xffff0000, v224
	v_lshlrev_b32_e32 v110, 16, v225
	v_and_b32_e32 v111, 0xffff0000, v225
	v_pk_mul_f32 v[110:111], v[218:219], v[110:111] op_sel_hi:[0,1]
	v_pk_mul_f32 v[108:109], v[218:219], v[108:109] op_sel_hi:[0,1]
	v_pk_fma_f32 v[104:105], v[108:109], v[188:189], v[104:105]
	v_pk_fma_f32 v[106:107], v[110:111], v[196:197], v[106:107]
	v_cndmask_b32_e32 v105, v105, v141, vcc
	v_cndmask_b32_e32 v107, v107, v141, vcc
	v_cndmask_b32_e32 v106, v106, v141, vcc
	v_cndmask_b32_e32 v104, v104, v141, vcc
	global_store_dwordx4 v[112:113], v[104:107], off offset:64 sc1
	s_nop 1
	v_lshlrev_b32_e32 v104, 16, v222
	v_and_b32_e32 v105, 0xffff0000, v222
	v_lshlrev_b32_e32 v106, 16, v223
	v_and_b32_e32 v107, 0xffff0000, v223
	v_pk_mul_f32 v[106:107], v[218:219], v[106:107] op_sel_hi:[0,1]
	v_pk_mul_f32 v[104:105], v[218:219], v[104:105] op_sel_hi:[0,1]
	v_pk_fma_f32 v[100:101], v[104:105], v[198:199], v[100:101]
	v_pk_fma_f32 v[102:103], v[106:107], v[204:205], v[102:103]
	v_cndmask_b32_e32 v101, v101, v141, vcc
	v_cndmask_b32_e32 v103, v103, v141, vcc
	v_cndmask_b32_e32 v102, v102, v141, vcc
	v_cndmask_b32_e32 v100, v100, v141, vcc
	global_store_dwordx4 v[112:113], v[100:103], off offset:512 sc1
	v_lshlrev_b32_e32 v104, 16, v217
	v_and_b32_e32 v105, 0xffff0000, v217
	v_lshlrev_b32_e32 v100, 16, v220
	v_and_b32_e32 v101, 0xffff0000, v220
	v_lshlrev_b32_e32 v102, 16, v221
	v_and_b32_e32 v103, 0xffff0000, v221
	v_pk_mul_f32 v[102:103], v[218:219], v[102:103] op_sel_hi:[0,1]
	v_pk_mul_f32 v[100:101], v[218:219], v[100:101] op_sel_hi:[0,1]
	v_pk_fma_f32 v[92:93], v[100:101], v[206:207], v[92:93]
	v_pk_fma_f32 v[94:95], v[102:103], v[212:213], v[94:95]
	v_cndmask_b32_e32 v93, v93, v141, vcc
	v_cndmask_b32_e32 v95, v95, v141, vcc
	v_cndmask_b32_e32 v94, v94, v141, vcc
	v_cndmask_b32_e32 v92, v92, v141, vcc
	global_store_dwordx4 v[112:113], v[92:95], off offset:576 sc1
	ds_read2_b64 v[92:95], v161 offset0:32 offset1:48
	v_add_u32_e32 v100, 32, v226
	v_ashrrev_i32_e32 v101, 31, v100
	v_lshlrev_b32_e32 v102, 16, v216
	v_and_b32_e32 v103, 0xffff0000, v216
	s_waitcnt lgkmcnt(0)
	v_pk_mul_f32 v[96:97], v[96:97], v[92:93] op_sel:[0,1]
	v_pk_mul_f32 v[98:99], v[98:99], v[92:93] op_sel:[0,1]
	v_pk_mul_f32 v[104:105], v[202:203], v[104:105] op_sel_hi:[0,1]
	v_pk_mul_f32 v[102:103], v[202:203], v[102:103] op_sel_hi:[0,1]
	v_pk_mul_f32 v[98:99], v[138:139], v[98:99]
	v_pk_mul_f32 v[96:97], v[136:137], v[96:97]
	v_lshlrev_b64 v[100:101], 12, v[100:101]
	v_pk_fma_f32 v[96:97], v[102:103], v[190:191], v[96:97]
	v_pk_fma_f32 v[98:99], v[104:105], v[192:193], v[98:99]
	v_lshl_add_u64 v[100:101], s[64:65], 0, v[100:101]
	v_cndmask_b32_e32 v99, v99, v141, vcc
	v_cndmask_b32_e32 v98, v98, v141, vcc
	v_cndmask_b32_e32 v97, v97, v141, vcc
	v_cndmask_b32_e32 v96, v96, v141, vcc
	v_lshl_add_u64 v[100:101], v[100:101], 0, v[172:173]
	global_store_dwordx4 v[100:101], v[96:99], off sc1
	v_pk_mul_f32 v[88:89], v[88:89], v[92:93] op_sel:[0,1]
	v_pk_mul_f32 v[90:91], v[90:91], v[92:93] op_sel:[0,1]
	v_lshlrev_b32_e32 v96, 16, v214
	v_and_b32_e32 v97, 0xffff0000, v214
	v_lshlrev_b32_e32 v98, 16, v215
	v_and_b32_e32 v99, 0xffff0000, v215
	v_pk_mul_f32 v[98:99], v[202:203], v[98:99] op_sel_hi:[0,1]
	v_pk_mul_f32 v[96:97], v[202:203], v[96:97] op_sel_hi:[0,1]
	v_pk_mul_f32 v[90:91], v[134:135], v[90:91]
	v_pk_mul_f32 v[88:89], v[132:133], v[88:89]
	v_pk_fma_f32 v[90:91], v[98:99], v[196:197], v[90:91]
	v_pk_fma_f32 v[88:89], v[96:97], v[188:189], v[88:89]
	v_cndmask_b32_e32 v91, v91, v141, vcc
	v_cndmask_b32_e32 v90, v90, v141, vcc
	v_cndmask_b32_e32 v89, v89, v141, vcc
	v_cndmask_b32_e32 v88, v88, v141, vcc
	global_store_dwordx4 v[100:101], v[88:91], off offset:64 sc1
	v_pk_mul_f32 v[84:85], v[84:85], v[92:93] op_sel:[0,1]
	v_pk_mul_f32 v[86:87], v[86:87], v[92:93] op_sel:[0,1]
	v_lshlrev_b32_e32 v88, 16, v210
	v_and_b32_e32 v89, 0xffff0000, v210
	v_lshlrev_b32_e32 v90, 16, v211
	v_and_b32_e32 v91, 0xffff0000, v211
	v_pk_mul_f32 v[90:91], v[202:203], v[90:91] op_sel_hi:[0,1]
	v_pk_mul_f32 v[88:89], v[202:203], v[88:89] op_sel_hi:[0,1]
	v_pk_mul_f32 v[86:87], v[130:131], v[86:87]
	v_pk_mul_f32 v[84:85], v[128:129], v[84:85]
	v_pk_fma_f32 v[86:87], v[90:91], v[204:205], v[86:87]
	v_pk_fma_f32 v[84:85], v[88:89], v[198:199], v[84:85]
	v_cndmask_b32_e32 v87, v87, v141, vcc
	v_cndmask_b32_e32 v86, v86, v141, vcc
	v_cndmask_b32_e32 v85, v85, v141, vcc
	v_cndmask_b32_e32 v84, v84, v141, vcc
	global_store_dwordx4 v[100:101], v[84:87], off offset:512 sc1
	v_pk_mul_f32 v[76:77], v[76:77], v[92:93] op_sel:[0,1]
	v_pk_mul_f32 v[78:79], v[78:79], v[92:93] op_sel:[0,1]
	v_lshlrev_b32_e32 v84, 16, v208
	v_and_b32_e32 v85, 0xffff0000, v208
	v_lshlrev_b32_e32 v86, 16, v209
	v_and_b32_e32 v87, 0xffff0000, v209
	v_pk_mul_f32 v[86:87], v[202:203], v[86:87] op_sel_hi:[0,1]
	v_pk_mul_f32 v[84:85], v[202:203], v[84:85] op_sel_hi:[0,1]
	v_pk_mul_f32 v[78:79], v[126:127], v[78:79]
	v_pk_mul_f32 v[76:77], v[124:125], v[76:77]
	v_pk_fma_f32 v[78:79], v[86:87], v[212:213], v[78:79]
	v_pk_fma_f32 v[76:77], v[84:85], v[206:207], v[76:77]
	v_cndmask_b32_e32 v79, v79, v141, vcc
	v_cndmask_b32_e32 v78, v78, v141, vcc
	v_cndmask_b32_e32 v77, v77, v141, vcc
	v_cndmask_b32_e32 v76, v76, v141, vcc
	global_store_dwordx4 v[100:101], v[76:79], off offset:576 sc1
	v_add_u32_e32 v84, 48, v226
	v_pk_mul_f32 v[80:81], v[80:81], v[94:95] op_sel:[0,1]
	v_lshlrev_b32_e32 v76, 16, v200
	v_and_b32_e32 v77, 0xffff0000, v200
	v_ashrrev_i32_e32 v85, 31, v84
	v_lshlrev_b32_e32 v78, 16, v201
	v_and_b32_e32 v79, 0xffff0000, v201
	v_pk_mul_f32 v[76:77], v[182:183], v[76:77] op_sel_hi:[0,1]
	v_pk_mul_f32 v[82:83], v[82:83], v[94:95] op_sel:[0,1]
	v_pk_mul_f32 v[80:81], v[136:137], v[80:81]
	v_pk_mul_f32 v[78:79], v[182:183], v[78:79] op_sel_hi:[0,1]
	v_pk_mul_f32 v[82:83], v[138:139], v[82:83]
	v_pk_fma_f32 v[76:77], v[76:77], v[190:191], v[80:81]
	v_lshlrev_b64 v[80:81], 12, v[84:85]
	v_pk_fma_f32 v[78:79], v[78:79], v[192:193], v[82:83]
	v_lshl_add_u64 v[80:81], s[64:65], 0, v[80:81]
	v_cndmask_b32_e32 v79, v79, v141, vcc
	v_cndmask_b32_e32 v78, v78, v141, vcc
	v_cndmask_b32_e32 v77, v77, v141, vcc
	v_cndmask_b32_e32 v76, v76, v141, vcc
	v_lshl_add_u64 v[80:81], v[80:81], 0, v[172:173]
	global_store_dwordx4 v[80:81], v[76:79], off sc1
	v_pk_mul_f32 v[72:73], v[72:73], v[94:95] op_sel:[0,1]
	v_pk_mul_f32 v[74:75], v[74:75], v[94:95] op_sel:[0,1]
	v_lshlrev_b32_e32 v76, 16, v194
	v_and_b32_e32 v77, 0xffff0000, v194
	v_lshlrev_b32_e32 v78, 16, v195
	v_and_b32_e32 v79, 0xffff0000, v195
	v_pk_mul_f32 v[78:79], v[182:183], v[78:79] op_sel_hi:[0,1]
	v_pk_mul_f32 v[76:77], v[182:183], v[76:77] op_sel_hi:[0,1]
	v_pk_mul_f32 v[74:75], v[134:135], v[74:75]
	v_pk_mul_f32 v[72:73], v[132:133], v[72:73]
	v_pk_fma_f32 v[74:75], v[78:79], v[196:197], v[74:75]
	v_pk_fma_f32 v[72:73], v[76:77], v[188:189], v[72:73]
	v_cndmask_b32_e32 v75, v75, v141, vcc
	v_cndmask_b32_e32 v74, v74, v141, vcc
	v_cndmask_b32_e32 v73, v73, v141, vcc
	v_cndmask_b32_e32 v72, v72, v141, vcc
	global_store_dwordx4 v[80:81], v[72:75], off offset:64 sc1
	v_pk_mul_f32 v[68:69], v[68:69], v[94:95] op_sel:[0,1]
	v_pk_mul_f32 v[70:71], v[70:71], v[94:95] op_sel:[0,1]
	v_lshlrev_b32_e32 v72, 16, v186
	v_and_b32_e32 v73, 0xffff0000, v186
	v_lshlrev_b32_e32 v74, 16, v187
	v_and_b32_e32 v75, 0xffff0000, v187
	v_pk_mul_f32 v[74:75], v[182:183], v[74:75] op_sel_hi:[0,1]
	v_pk_mul_f32 v[72:73], v[182:183], v[72:73] op_sel_hi:[0,1]
	v_pk_mul_f32 v[70:71], v[130:131], v[70:71]
	v_pk_mul_f32 v[68:69], v[128:129], v[68:69]
	v_pk_fma_f32 v[70:71], v[74:75], v[204:205], v[70:71]
	v_pk_fma_f32 v[68:69], v[72:73], v[198:199], v[68:69]
	v_cndmask_b32_e32 v71, v71, v141, vcc
	v_cndmask_b32_e32 v70, v70, v141, vcc
	v_cndmask_b32_e32 v69, v69, v141, vcc
	v_cndmask_b32_e32 v68, v68, v141, vcc
	global_store_dwordx4 v[80:81], v[68:71], off offset:512 sc1
	v_pk_mul_f32 v[64:65], v[64:65], v[94:95] op_sel:[0,1]
	v_pk_mul_f32 v[66:67], v[66:67], v[94:95] op_sel:[0,1]
	v_lshlrev_b32_e32 v68, 16, v184
	v_and_b32_e32 v69, 0xffff0000, v184
	v_lshlrev_b32_e32 v70, 16, v185
	v_and_b32_e32 v71, 0xffff0000, v185
	v_pk_mul_f32 v[70:71], v[182:183], v[70:71] op_sel_hi:[0,1]
	v_pk_mul_f32 v[68:69], v[182:183], v[68:69] op_sel_hi:[0,1]
	v_pk_mul_f32 v[66:67], v[126:127], v[66:67]
	v_pk_mul_f32 v[64:65], v[124:125], v[64:65]
	v_pk_fma_f32 v[66:67], v[70:71], v[212:213], v[66:67]
	v_pk_fma_f32 v[64:65], v[68:69], v[206:207], v[64:65]
	v_cndmask_b32_e32 v67, v67, v141, vcc
	v_cndmask_b32_e32 v66, v66, v141, vcc
	v_cndmask_b32_e32 v65, v65, v141, vcc
	v_cndmask_b32_e32 v64, v64, v141, vcc
	global_store_dwordx4 v[80:81], v[64:67], off offset:576 sc1
	ds_read2_b64 v[64:67], v161 offset0:128 offset1:144
	v_add_u32_e32 v68, 0x80, v226
	v_ashrrev_i32_e32 v69, 31, v68
	v_lshlrev_b32_e32 v70, 16, v180
	v_and_b32_e32 v71, 0xffff0000, v180
	v_lshlrev_b32_e32 v72, 16, v181
	v_and_b32_e32 v73, 0xffff0000, v181
	s_waitcnt lgkmcnt(0)
	v_pk_mul_f32 v[60:61], v[60:61], v[64:65] op_sel:[0,1]
	v_pk_mul_f32 v[62:63], v[62:63], v[64:65] op_sel:[0,1]
	v_pk_mul_f32 v[72:73], v[170:171], v[72:73] op_sel_hi:[0,1]
	v_pk_mul_f32 v[70:71], v[170:171], v[70:71] op_sel_hi:[0,1]
	v_pk_mul_f32 v[62:63], v[138:139], v[62:63]
	v_pk_mul_f32 v[60:61], v[136:137], v[60:61]
	v_lshlrev_b64 v[68:69], 12, v[68:69]
	v_pk_fma_f32 v[60:61], v[70:71], v[190:191], v[60:61]
	v_pk_fma_f32 v[62:63], v[72:73], v[192:193], v[62:63]
	v_lshl_add_u64 v[68:69], s[64:65], 0, v[68:69]
	v_cndmask_b32_e32 v63, v63, v141, vcc
	v_cndmask_b32_e32 v62, v62, v141, vcc
	v_cndmask_b32_e32 v61, v61, v141, vcc
	v_cndmask_b32_e32 v60, v60, v141, vcc
	v_lshl_add_u64 v[68:69], v[68:69], 0, v[172:173]
	global_store_dwordx4 v[68:69], v[60:63], off sc1
	v_pk_mul_f32 v[56:57], v[56:57], v[64:65] op_sel:[0,1]
	v_pk_mul_f32 v[58:59], v[58:59], v[64:65] op_sel:[0,1]
	v_lshlrev_b32_e32 v60, 16, v178
	v_and_b32_e32 v61, 0xffff0000, v178
	v_lshlrev_b32_e32 v62, 16, v179
	v_and_b32_e32 v63, 0xffff0000, v179
	v_pk_mul_f32 v[62:63], v[170:171], v[62:63] op_sel_hi:[0,1]
	v_pk_mul_f32 v[60:61], v[170:171], v[60:61] op_sel_hi:[0,1]
	v_pk_mul_f32 v[58:59], v[134:135], v[58:59]
	v_pk_mul_f32 v[56:57], v[132:133], v[56:57]
	v_pk_fma_f32 v[58:59], v[62:63], v[196:197], v[58:59]
	v_pk_fma_f32 v[56:57], v[60:61], v[188:189], v[56:57]
	v_cndmask_b32_e32 v59, v59, v141, vcc
	v_cndmask_b32_e32 v58, v58, v141, vcc
	v_cndmask_b32_e32 v57, v57, v141, vcc
	v_cndmask_b32_e32 v56, v56, v141, vcc
	global_store_dwordx4 v[68:69], v[56:59], off offset:64 sc1
	v_pk_mul_f32 v[52:53], v[52:53], v[64:65] op_sel:[0,1]
	v_pk_mul_f32 v[54:55], v[54:55], v[64:65] op_sel:[0,1]
	v_lshlrev_b32_e32 v56, 16, v176
	v_and_b32_e32 v57, 0xffff0000, v176
	v_lshlrev_b32_e32 v58, 16, v177
	v_and_b32_e32 v59, 0xffff0000, v177
	v_pk_mul_f32 v[58:59], v[170:171], v[58:59] op_sel_hi:[0,1]
	v_pk_mul_f32 v[56:57], v[170:171], v[56:57] op_sel_hi:[0,1]
	v_pk_mul_f32 v[54:55], v[130:131], v[54:55]
	v_pk_mul_f32 v[52:53], v[128:129], v[52:53]
	v_pk_fma_f32 v[54:55], v[58:59], v[204:205], v[54:55]
	v_pk_fma_f32 v[52:53], v[56:57], v[198:199], v[52:53]
	v_cndmask_b32_e32 v55, v55, v141, vcc
	v_cndmask_b32_e32 v54, v54, v141, vcc
	v_cndmask_b32_e32 v53, v53, v141, vcc
	v_cndmask_b32_e32 v52, v52, v141, vcc
	global_store_dwordx4 v[68:69], v[52:55], off offset:512 sc1
	v_pk_mul_f32 v[44:45], v[44:45], v[64:65] op_sel:[0,1]
	v_pk_mul_f32 v[46:47], v[46:47], v[64:65] op_sel:[0,1]
	v_lshlrev_b32_e32 v52, 16, v174
	v_and_b32_e32 v53, 0xffff0000, v174
	v_lshlrev_b32_e32 v54, 16, v175
	v_and_b32_e32 v55, 0xffff0000, v175
	v_pk_mul_f32 v[54:55], v[170:171], v[54:55] op_sel_hi:[0,1]
	v_pk_mul_f32 v[52:53], v[170:171], v[52:53] op_sel_hi:[0,1]
	v_pk_mul_f32 v[46:47], v[126:127], v[46:47]
	v_pk_mul_f32 v[44:45], v[124:125], v[44:45]
	v_pk_fma_f32 v[46:47], v[54:55], v[212:213], v[46:47]
	v_pk_fma_f32 v[44:45], v[52:53], v[206:207], v[44:45]
	v_cndmask_b32_e32 v47, v47, v141, vcc
	v_cndmask_b32_e32 v46, v46, v141, vcc
	v_cndmask_b32_e32 v45, v45, v141, vcc
	v_cndmask_b32_e32 v44, v44, v141, vcc
	global_store_dwordx4 v[68:69], v[44:47], off offset:576 sc1
	v_add_u32_e32 v52, 0x90, v226
	v_pk_mul_f32 v[48:49], v[48:49], v[66:67] op_sel:[0,1]
	v_lshlrev_b32_e32 v44, 16, v168
	v_and_b32_e32 v45, 0xffff0000, v168
	v_ashrrev_i32_e32 v53, 31, v52
	v_lshlrev_b32_e32 v46, 16, v169
	v_and_b32_e32 v47, 0xffff0000, v169
	v_pk_mul_f32 v[44:45], v[160:161], v[44:45] op_sel_hi:[0,1]
	v_pk_mul_f32 v[50:51], v[50:51], v[66:67] op_sel:[0,1]
	v_pk_mul_f32 v[48:49], v[136:137], v[48:49]
	v_pk_mul_f32 v[46:47], v[160:161], v[46:47] op_sel_hi:[0,1]
	v_pk_mul_f32 v[50:51], v[138:139], v[50:51]
	v_pk_fma_f32 v[44:45], v[44:45], v[190:191], v[48:49]
	v_lshlrev_b64 v[48:49], 12, v[52:53]
	v_pk_fma_f32 v[46:47], v[46:47], v[192:193], v[50:51]
	v_lshl_add_u64 v[48:49], s[64:65], 0, v[48:49]
	v_cndmask_b32_e32 v47, v47, v141, vcc
	v_cndmask_b32_e32 v46, v46, v141, vcc
	v_cndmask_b32_e32 v45, v45, v141, vcc
	v_cndmask_b32_e32 v44, v44, v141, vcc
	v_lshl_add_u64 v[48:49], v[48:49], 0, v[172:173]
	global_store_dwordx4 v[48:49], v[44:47], off sc1
	v_pk_mul_f32 v[40:41], v[40:41], v[66:67] op_sel:[0,1]
	v_pk_mul_f32 v[42:43], v[42:43], v[66:67] op_sel:[0,1]
	v_lshlrev_b32_e32 v44, 16, v166
	v_and_b32_e32 v45, 0xffff0000, v166
	v_lshlrev_b32_e32 v46, 16, v167
	v_and_b32_e32 v47, 0xffff0000, v167
	v_pk_mul_f32 v[46:47], v[160:161], v[46:47] op_sel_hi:[0,1]
	v_pk_mul_f32 v[44:45], v[160:161], v[44:45] op_sel_hi:[0,1]
	v_pk_mul_f32 v[42:43], v[134:135], v[42:43]
	v_pk_mul_f32 v[40:41], v[132:133], v[40:41]
	v_pk_fma_f32 v[42:43], v[46:47], v[196:197], v[42:43]
	v_pk_fma_f32 v[40:41], v[44:45], v[188:189], v[40:41]
	v_cndmask_b32_e32 v43, v43, v141, vcc
	v_cndmask_b32_e32 v42, v42, v141, vcc
	v_cndmask_b32_e32 v41, v41, v141, vcc
	v_cndmask_b32_e32 v40, v40, v141, vcc
	global_store_dwordx4 v[48:49], v[40:43], off offset:64 sc1
	v_pk_mul_f32 v[36:37], v[36:37], v[66:67] op_sel:[0,1]
	v_pk_mul_f32 v[38:39], v[38:39], v[66:67] op_sel:[0,1]
	v_lshlrev_b32_e32 v40, 16, v164
	v_and_b32_e32 v41, 0xffff0000, v164
	v_lshlrev_b32_e32 v42, 16, v165
	v_and_b32_e32 v43, 0xffff0000, v165
	v_pk_mul_f32 v[42:43], v[160:161], v[42:43] op_sel_hi:[0,1]
	v_pk_mul_f32 v[40:41], v[160:161], v[40:41] op_sel_hi:[0,1]
	v_pk_mul_f32 v[38:39], v[130:131], v[38:39]
	v_pk_mul_f32 v[36:37], v[128:129], v[36:37]
	v_pk_fma_f32 v[38:39], v[42:43], v[204:205], v[38:39]
	v_pk_fma_f32 v[36:37], v[40:41], v[198:199], v[36:37]
	v_cndmask_b32_e32 v39, v39, v141, vcc
	v_cndmask_b32_e32 v38, v38, v141, vcc
	v_cndmask_b32_e32 v37, v37, v141, vcc
	v_cndmask_b32_e32 v36, v36, v141, vcc
	global_store_dwordx4 v[48:49], v[36:39], off offset:512 sc1
	v_pk_mul_f32 v[28:29], v[28:29], v[66:67] op_sel:[0,1]
	v_pk_mul_f32 v[30:31], v[30:31], v[66:67] op_sel:[0,1]
	v_lshlrev_b32_e32 v36, 16, v162
	v_and_b32_e32 v37, 0xffff0000, v162
	v_lshlrev_b32_e32 v38, 16, v163
	v_and_b32_e32 v39, 0xffff0000, v163
	v_pk_mul_f32 v[38:39], v[160:161], v[38:39] op_sel_hi:[0,1]
	v_pk_mul_f32 v[36:37], v[160:161], v[36:37] op_sel_hi:[0,1]
	v_pk_mul_f32 v[30:31], v[126:127], v[30:31]
	v_pk_mul_f32 v[28:29], v[124:125], v[28:29]
	v_pk_fma_f32 v[30:31], v[38:39], v[212:213], v[30:31]
	v_pk_fma_f32 v[28:29], v[36:37], v[206:207], v[28:29]
	v_cndmask_b32_e32 v31, v31, v141, vcc
	v_cndmask_b32_e32 v30, v30, v141, vcc
	v_cndmask_b32_e32 v29, v29, v141, vcc
	v_cndmask_b32_e32 v28, v28, v141, vcc
	global_store_dwordx4 v[48:49], v[28:31], off offset:576 sc1
	ds_read2_b64 v[28:31], v161 offset0:160 offset1:176
	v_add_u32_e32 v36, 0xa0, v226
	v_ashrrev_i32_e32 v37, 31, v36
	v_lshlrev_b32_e32 v38, 16, v158
	v_and_b32_e32 v39, 0xffff0000, v158
	v_lshlrev_b32_e32 v40, 16, v159
	v_and_b32_e32 v41, 0xffff0000, v159
	s_waitcnt lgkmcnt(0)
	v_pk_mul_f32 v[32:33], v[32:33], v[28:29] op_sel:[0,1]
	v_pk_mul_f32 v[34:35], v[34:35], v[28:29] op_sel:[0,1]
	v_pk_mul_f32 v[40:41], v[150:151], v[40:41] op_sel_hi:[0,1]
	v_pk_mul_f32 v[38:39], v[150:151], v[38:39] op_sel_hi:[0,1]
	v_pk_mul_f32 v[34:35], v[138:139], v[34:35]
	v_pk_mul_f32 v[32:33], v[136:137], v[32:33]
	v_lshlrev_b64 v[36:37], 12, v[36:37]
	v_pk_fma_f32 v[32:33], v[38:39], v[190:191], v[32:33]
	v_pk_fma_f32 v[34:35], v[40:41], v[192:193], v[34:35]
	v_lshl_add_u64 v[36:37], s[64:65], 0, v[36:37]
	v_cndmask_b32_e32 v35, v35, v141, vcc
	v_cndmask_b32_e32 v34, v34, v141, vcc
	v_cndmask_b32_e32 v33, v33, v141, vcc
	v_cndmask_b32_e32 v32, v32, v141, vcc
	v_lshl_add_u64 v[36:37], v[36:37], 0, v[172:173]
	global_store_dwordx4 v[36:37], v[32:35], off sc1
	v_pk_mul_f32 v[24:25], v[24:25], v[28:29] op_sel:[0,1]
	v_pk_mul_f32 v[26:27], v[26:27], v[28:29] op_sel:[0,1]
	v_lshlrev_b32_e32 v32, 16, v156
	v_and_b32_e32 v33, 0xffff0000, v156
	v_lshlrev_b32_e32 v34, 16, v157
	v_and_b32_e32 v35, 0xffff0000, v157
	v_pk_mul_f32 v[34:35], v[150:151], v[34:35] op_sel_hi:[0,1]
	v_pk_mul_f32 v[32:33], v[150:151], v[32:33] op_sel_hi:[0,1]
	v_pk_mul_f32 v[26:27], v[134:135], v[26:27]
	v_pk_mul_f32 v[24:25], v[132:133], v[24:25]
	v_pk_fma_f32 v[26:27], v[34:35], v[196:197], v[26:27]
	v_pk_fma_f32 v[24:25], v[32:33], v[188:189], v[24:25]
	v_cndmask_b32_e32 v27, v27, v141, vcc
	v_cndmask_b32_e32 v26, v26, v141, vcc
	v_cndmask_b32_e32 v25, v25, v141, vcc
	v_cndmask_b32_e32 v24, v24, v141, vcc
	global_store_dwordx4 v[36:37], v[24:27], off offset:64 sc1
	v_pk_mul_f32 v[20:21], v[20:21], v[28:29] op_sel:[0,1]
	v_pk_mul_f32 v[22:23], v[22:23], v[28:29] op_sel:[0,1]
	v_lshlrev_b32_e32 v24, 16, v154
	v_and_b32_e32 v25, 0xffff0000, v154
	v_lshlrev_b32_e32 v26, 16, v155
	v_and_b32_e32 v27, 0xffff0000, v155
	v_pk_mul_f32 v[26:27], v[150:151], v[26:27] op_sel_hi:[0,1]
	v_pk_mul_f32 v[24:25], v[150:151], v[24:25] op_sel_hi:[0,1]
	v_pk_mul_f32 v[22:23], v[130:131], v[22:23]
	v_pk_mul_f32 v[20:21], v[128:129], v[20:21]
	v_pk_fma_f32 v[22:23], v[26:27], v[204:205], v[22:23]
	v_pk_fma_f32 v[20:21], v[24:25], v[198:199], v[20:21]
	v_cndmask_b32_e32 v23, v23, v141, vcc
	v_cndmask_b32_e32 v22, v22, v141, vcc
	v_cndmask_b32_e32 v21, v21, v141, vcc
	v_cndmask_b32_e32 v20, v20, v141, vcc
	global_store_dwordx4 v[36:37], v[20:23], off offset:512 sc1
	v_pk_mul_f32 v[12:13], v[12:13], v[28:29] op_sel:[0,1]
	v_pk_mul_f32 v[14:15], v[14:15], v[28:29] op_sel:[0,1]
	v_lshlrev_b32_e32 v20, 16, v152
	v_and_b32_e32 v21, 0xffff0000, v152
	v_lshlrev_b32_e32 v22, 16, v153
	v_and_b32_e32 v23, 0xffff0000, v153
	v_pk_mul_f32 v[22:23], v[150:151], v[22:23] op_sel_hi:[0,1]
	v_pk_mul_f32 v[20:21], v[150:151], v[20:21] op_sel_hi:[0,1]
	v_pk_mul_f32 v[14:15], v[126:127], v[14:15]
	v_pk_mul_f32 v[12:13], v[124:125], v[12:13]
	v_pk_fma_f32 v[14:15], v[22:23], v[212:213], v[14:15]
	v_pk_fma_f32 v[12:13], v[20:21], v[206:207], v[12:13]
	v_cndmask_b32_e32 v15, v15, v141, vcc
	v_cndmask_b32_e32 v14, v14, v141, vcc
	v_cndmask_b32_e32 v13, v13, v141, vcc
	v_cndmask_b32_e32 v12, v12, v141, vcc
	global_store_dwordx4 v[36:37], v[12:15], off offset:576 sc1
	v_add_u32_e32 v20, 0xb0, v226
	v_pk_mul_f32 v[16:17], v[16:17], v[30:31] op_sel:[0,1]
	v_lshlrev_b32_e32 v12, 16, v148
	v_and_b32_e32 v13, 0xffff0000, v148
	v_ashrrev_i32_e32 v21, 31, v20
	v_lshlrev_b32_e32 v14, 16, v149
	v_and_b32_e32 v15, 0xffff0000, v149
	v_pk_mul_f32 v[12:13], v[140:141], v[12:13] op_sel_hi:[0,1]
	v_pk_mul_f32 v[18:19], v[18:19], v[30:31] op_sel:[0,1]
	v_pk_mul_f32 v[16:17], v[136:137], v[16:17]
	v_pk_mul_f32 v[14:15], v[140:141], v[14:15] op_sel_hi:[0,1]
	v_pk_mul_f32 v[18:19], v[138:139], v[18:19]
	v_pk_fma_f32 v[12:13], v[12:13], v[190:191], v[16:17]
	v_lshlrev_b64 v[16:17], 12, v[20:21]
	v_pk_fma_f32 v[14:15], v[14:15], v[192:193], v[18:19]
	v_lshl_add_u64 v[16:17], s[64:65], 0, v[16:17]
	v_cndmask_b32_e32 v15, v15, v141, vcc
	v_cndmask_b32_e32 v14, v14, v141, vcc
	v_cndmask_b32_e32 v13, v13, v141, vcc
	v_cndmask_b32_e32 v12, v12, v141, vcc
	v_lshl_add_u64 v[16:17], v[16:17], 0, v[172:173]
	global_store_dwordx4 v[16:17], v[12:15], off sc1
	v_pk_mul_f32 v[8:9], v[8:9], v[30:31] op_sel:[0,1]
	v_pk_mul_f32 v[10:11], v[10:11], v[30:31] op_sel:[0,1]
	v_lshlrev_b32_e32 v12, 16, v146
	v_and_b32_e32 v13, 0xffff0000, v146
	v_lshlrev_b32_e32 v14, 16, v147
	v_and_b32_e32 v15, 0xffff0000, v147
	v_pk_mul_f32 v[14:15], v[140:141], v[14:15] op_sel_hi:[0,1]
	v_pk_mul_f32 v[12:13], v[140:141], v[12:13] op_sel_hi:[0,1]
	v_pk_mul_f32 v[10:11], v[134:135], v[10:11]
	v_pk_mul_f32 v[8:9], v[132:133], v[8:9]
	v_pk_fma_f32 v[10:11], v[14:15], v[196:197], v[10:11]
	v_pk_fma_f32 v[8:9], v[12:13], v[188:189], v[8:9]
	v_cndmask_b32_e32 v11, v11, v141, vcc
	v_cndmask_b32_e32 v10, v10, v141, vcc
	v_cndmask_b32_e32 v9, v9, v141, vcc
	v_cndmask_b32_e32 v8, v8, v141, vcc
	global_store_dwordx4 v[16:17], v[8:11], off offset:64 sc1
	v_pk_mul_f32 v[4:5], v[4:5], v[30:31] op_sel:[0,1]
	v_pk_mul_f32 v[6:7], v[6:7], v[30:31] op_sel:[0,1]
	v_lshlrev_b32_e32 v8, 16, v144
	v_and_b32_e32 v9, 0xffff0000, v144
	v_lshlrev_b32_e32 v10, 16, v145
	v_and_b32_e32 v11, 0xffff0000, v145
	v_pk_mul_f32 v[10:11], v[140:141], v[10:11] op_sel_hi:[0,1]
	v_pk_mul_f32 v[8:9], v[140:141], v[8:9] op_sel_hi:[0,1]
	v_pk_mul_f32 v[6:7], v[130:131], v[6:7]
	v_pk_mul_f32 v[4:5], v[128:129], v[4:5]
	v_pk_fma_f32 v[6:7], v[10:11], v[204:205], v[6:7]
	v_pk_fma_f32 v[4:5], v[8:9], v[198:199], v[4:5]
	v_cndmask_b32_e32 v7, v7, v141, vcc
	v_cndmask_b32_e32 v6, v6, v141, vcc
	v_cndmask_b32_e32 v5, v5, v141, vcc
	v_cndmask_b32_e32 v4, v4, v141, vcc
	global_store_dwordx4 v[16:17], v[4:7], off offset:512 sc1
	v_pk_mul_f32 v[0:1], v[0:1], v[30:31] op_sel:[0,1]
	v_pk_mul_f32 v[2:3], v[2:3], v[30:31] op_sel:[0,1]
	v_lshlrev_b32_e32 v4, 16, v142
	v_and_b32_e32 v5, 0xffff0000, v142
	v_lshlrev_b32_e32 v6, 16, v143
	v_and_b32_e32 v7, 0xffff0000, v143
	v_pk_mul_f32 v[6:7], v[140:141], v[6:7] op_sel_hi:[0,1]
	v_pk_mul_f32 v[4:5], v[140:141], v[4:5] op_sel_hi:[0,1]
	v_pk_mul_f32 v[2:3], v[126:127], v[2:3]
	v_pk_mul_f32 v[0:1], v[124:125], v[0:1]
	v_pk_fma_f32 v[2:3], v[6:7], v[212:213], v[2:3]
	v_pk_fma_f32 v[0:1], v[4:5], v[206:207], v[0:1]
	v_cndmask_b32_e32 v3, v3, v141, vcc
	v_cndmask_b32_e32 v2, v2, v141, vcc
	v_cndmask_b32_e32 v1, v1, v141, vcc
	v_cndmask_b32_e32 v0, v0, v141, vcc
	global_store_dwordx4 v[16:17], v[0:3], off offset:576 sc1
